# comb12 + final-norm output ladder: the four gain quads loaded once, 32 f32 output stores issued back to back (no per-chunk load / vmcnt(0) store drain)
# baseline (speedup 1.0000x reference)
;     __device__ __forceinline__ void operator()(f32x4 (&acc)[2][2][4][2], const Unit& u, int wr, int wc, int fr, int fq) const {
;     ...
;         asm volatile("s_waitcnt vmcnt(0) lgkmcnt(0)" ::: "memory"); __builtin_amdgcn_s_barrier(); asm volatile("" ::: "memory");
; #pragma unroll
;         for (int ai = 0; ai < 2; ++ai)
; #pragma unroll
;             for (int m = 0; m < 4; ++m) { const int rl = ai * HALF + wr * 64 + m * 16 + fr; const float rstd = R[rl]; float* orow = out + (size_t)(u.pm * BM + rl) * D + col0;
; #pragma unroll
;                 for (int bj = 0; bj < 2; ++bj) { const f32x4 g0 = *(const f32x4*)(gain + col0 + bj * HALF), g1 = *(const f32x4*)(gain + col0 + bj * HALF + 4);
;                     *(f32x4*)(orow + bj * HALF) = acc[ai][bj][m][0] * rstd * g0; *(f32x4*)(orow + bj * HALF + 4) = acc[ai][bj][m][1] * rstd * g1; } }
.LBB0_1314:
	s_or_b64 exec, exec, s[54:55]
	v_lshlrev_b64 v[158:159], 2, v[148:149]
	s_waitcnt vmcnt(0) lgkmcnt(0)
	s_barrier
	v_lshl_add_u64 v[148:149], s[22:23], 0, v[158:159]
	global_load_dwordx4 v[188:191], v[148:149], off
	global_load_dwordx4 v[192:195], v[148:149], off offset:16
	global_load_dwordx4 v[196:199], v[148:149], off offset:512
	global_load_dwordx4 v[200:203], v[148:149], off offset:528
	s_waitcnt lgkmcnt(0)
	s_nop 0
	v_lshlrev_b64 v[146:147], 13, v[146:147]
	v_lshl_add_u64 v[146:147], s[12:13], 0, v[146:147]
	ds_read_b32 v136, v178
	ds_read_b32 v160, v179
	ds_read_b32 v162, v180
	ds_read_b32 v164, v181
	ds_read_b32 v166, v182
	ds_read_b32 v168, v183
	ds_read_b32 v172, v184
	ds_read_b32 v170, v185
	s_waitcnt lgkmcnt(7)
	v_pk_mul_f32 v[126:127], v[126:127], v[136:137] op_sel_hi:[1,0]
	v_pk_mul_f32 v[124:125], v[124:125], v[136:137] op_sel_hi:[1,0]
	v_lshl_add_u64 v[146:147], v[146:147], 0, v[158:159]
	v_pk_mul_f32 v[122:123], v[122:123], v[136:137] op_sel_hi:[1,0]
	v_pk_mul_f32 v[120:121], v[120:121], v[136:137] op_sel_hi:[1,0]
	v_pk_mul_f32 v[118:119], v[118:119], v[136:137] op_sel_hi:[1,0]
	v_pk_mul_f32 v[116:117], v[116:117], v[136:137] op_sel_hi:[1,0]
	v_pk_mul_f32 v[114:115], v[114:115], v[136:137] op_sel_hi:[1,0]
	v_pk_mul_f32 v[112:113], v[112:113], v[136:137] op_sel_hi:[1,0]
	s_waitcnt lgkmcnt(6)
	v_pk_mul_f32 v[110:111], v[110:111], v[160:161] op_sel_hi:[1,0]
	v_pk_mul_f32 v[108:109], v[108:109], v[160:161] op_sel_hi:[1,0]
	v_pk_mul_f32 v[106:107], v[106:107], v[160:161] op_sel_hi:[1,0]
	v_pk_mul_f32 v[104:105], v[104:105], v[160:161] op_sel_hi:[1,0]
	v_pk_mul_f32 v[102:103], v[102:103], v[160:161] op_sel_hi:[1,0]
	v_pk_mul_f32 v[100:101], v[100:101], v[160:161] op_sel_hi:[1,0]
	v_pk_mul_f32 v[98:99], v[98:99], v[160:161] op_sel_hi:[1,0]
	v_pk_mul_f32 v[96:97], v[96:97], v[160:161] op_sel_hi:[1,0]
	s_waitcnt lgkmcnt(5)
	v_pk_mul_f32 v[94:95], v[94:95], v[162:163] op_sel_hi:[1,0]
	v_pk_mul_f32 v[92:93], v[92:93], v[162:163] op_sel_hi:[1,0]
	v_pk_mul_f32 v[90:91], v[90:91], v[162:163] op_sel_hi:[1,0]
	v_pk_mul_f32 v[88:89], v[88:89], v[162:163] op_sel_hi:[1,0]
	v_pk_mul_f32 v[86:87], v[86:87], v[162:163] op_sel_hi:[1,0]
	v_pk_mul_f32 v[84:85], v[84:85], v[162:163] op_sel_hi:[1,0]
	v_pk_mul_f32 v[82:83], v[82:83], v[162:163] op_sel_hi:[1,0]
	v_pk_mul_f32 v[80:81], v[80:81], v[162:163] op_sel_hi:[1,0]
	s_waitcnt lgkmcnt(4)
	v_pk_mul_f32 v[78:79], v[78:79], v[164:165] op_sel_hi:[1,0]
	v_pk_mul_f32 v[76:77], v[76:77], v[164:165] op_sel_hi:[1,0]
	v_pk_mul_f32 v[74:75], v[74:75], v[164:165] op_sel_hi:[1,0]
	v_pk_mul_f32 v[72:73], v[72:73], v[164:165] op_sel_hi:[1,0]
	v_pk_mul_f32 v[70:71], v[70:71], v[164:165] op_sel_hi:[1,0]
	v_pk_mul_f32 v[68:69], v[68:69], v[164:165] op_sel_hi:[1,0]
	v_pk_mul_f32 v[66:67], v[66:67], v[164:165] op_sel_hi:[1,0]
	v_pk_mul_f32 v[64:65], v[64:65], v[164:165] op_sel_hi:[1,0]
	s_waitcnt lgkmcnt(3)
	v_pk_mul_f32 v[62:63], v[62:63], v[166:167] op_sel_hi:[1,0]
	v_pk_mul_f32 v[60:61], v[60:61], v[166:167] op_sel_hi:[1,0]
	v_pk_mul_f32 v[58:59], v[58:59], v[166:167] op_sel_hi:[1,0]
	v_pk_mul_f32 v[56:57], v[56:57], v[166:167] op_sel_hi:[1,0]
	v_pk_mul_f32 v[54:55], v[54:55], v[166:167] op_sel_hi:[1,0]
	v_pk_mul_f32 v[52:53], v[52:53], v[166:167] op_sel_hi:[1,0]
	v_pk_mul_f32 v[50:51], v[50:51], v[166:167] op_sel_hi:[1,0]
	v_pk_mul_f32 v[48:49], v[48:49], v[166:167] op_sel_hi:[1,0]
	s_waitcnt lgkmcnt(2)
	v_pk_mul_f32 v[46:47], v[46:47], v[168:169] op_sel_hi:[1,0]
	v_pk_mul_f32 v[44:45], v[44:45], v[168:169] op_sel_hi:[1,0]
	v_pk_mul_f32 v[42:43], v[42:43], v[168:169] op_sel_hi:[1,0]
	v_pk_mul_f32 v[40:41], v[40:41], v[168:169] op_sel_hi:[1,0]
	v_pk_mul_f32 v[38:39], v[38:39], v[168:169] op_sel_hi:[1,0]
	v_pk_mul_f32 v[36:37], v[36:37], v[168:169] op_sel_hi:[1,0]
	v_pk_mul_f32 v[34:35], v[34:35], v[168:169] op_sel_hi:[1,0]
	v_pk_mul_f32 v[32:33], v[32:33], v[168:169] op_sel_hi:[1,0]
	s_waitcnt lgkmcnt(1)
	v_pk_mul_f32 v[30:31], v[30:31], v[172:173] op_sel_hi:[1,0]
	v_pk_mul_f32 v[28:29], v[28:29], v[172:173] op_sel_hi:[1,0]
	v_pk_mul_f32 v[26:27], v[26:27], v[172:173] op_sel_hi:[1,0]
	v_pk_mul_f32 v[24:25], v[24:25], v[172:173] op_sel_hi:[1,0]
	v_pk_mul_f32 v[22:23], v[22:23], v[172:173] op_sel_hi:[1,0]
	v_pk_mul_f32 v[20:21], v[20:21], v[172:173] op_sel_hi:[1,0]
	v_pk_mul_f32 v[18:19], v[18:19], v[172:173] op_sel_hi:[1,0]
	v_pk_mul_f32 v[16:17], v[16:17], v[172:173] op_sel_hi:[1,0]
	s_waitcnt lgkmcnt(0)
	v_pk_mul_f32 v[8:9], v[8:9], v[170:171] op_sel_hi:[1,0]
	v_pk_mul_f32 v[10:11], v[10:11], v[170:171] op_sel_hi:[1,0]
	s_andn2_b64 vcc, exec, s[8:9]
	v_pk_mul_f32 v[12:13], v[12:13], v[170:171] op_sel_hi:[1,0]
	v_pk_mul_f32 v[14:15], v[14:15], v[170:171] op_sel_hi:[1,0]
	s_mov_b64 s[8:9], -1
	s_waitcnt vmcnt(0)
;     __device__ __forceinline__ void operator()(f32x4 (&acc)[2][2][4][2], const Unit& u, int wr, int wc, int fr, int fq) const {
;     ...
;             for (int m = 0; m < 4; ++m) { const int rl = ai * HALF + wr * 64 + m * 16 + fr; const float rstd = R[rl]; float* orow = out + (size_t)(u.pm * BM + rl) * D + col0;
; #pragma unroll
;                 for (int bj = 0; bj < 2; ++bj) { const f32x4 g0 = *(const f32x4*)(gain + col0 + bj * HALF), g1 = *(const f32x4*)(gain + col0 + bj * HALF + 4);
;                     *(f32x4*)(orow + bj * HALF) = acc[ai][bj][m][0] * rstd * g0; *(f32x4*)(orow + bj * HALF + 4) = acc[ai][bj][m][1] * rstd * g1; } }
	v_pk_mul_f32 v[6:7], v[190:191], v[126:127]
	v_pk_mul_f32 v[4:5], v[188:189], v[124:125]
	s_nop 0
	v_pk_mul_f32 v[2:3], v[194:195], v[122:123]
	v_pk_mul_f32 v[0:1], v[192:193], v[120:121]
	global_store_dwordx4 v[146:147], v[4:7], off
	global_store_dwordx4 v[146:147], v[0:3], off offset:16
	s_nop 0
	s_nop 0
	s_nop 0
	s_nop 0
	v_pk_mul_f32 v[2:3], v[118:119], v[198:199]
	v_pk_mul_f32 v[0:1], v[116:117], v[196:197]
	s_nop 0
	v_pk_mul_f32 v[6:7], v[114:115], v[202:203]
	v_pk_mul_f32 v[4:5], v[112:113], v[200:201]
	global_store_dwordx4 v[146:147], v[0:3], off offset:512
	global_store_dwordx4 v[146:147], v[4:7], off offset:528
	s_nop 0
	s_nop 0
	s_nop 0
	v_add_u32_e32 v112, s39, v167
	v_ashrrev_i32_e32 v113, 31, v112
	v_lshlrev_b64 v[112:113], 13, v[112:113]
	v_lshl_add_u64 v[112:113], s[12:13], 0, v[112:113]
	v_lshl_add_u64 v[112:113], v[112:113], 0, v[158:159]
	s_nop 0
	v_pk_mul_f32 v[2:3], v[190:191], v[110:111]
	v_pk_mul_f32 v[0:1], v[188:189], v[108:109]
	s_nop 0
	v_pk_mul_f32 v[6:7], v[194:195], v[106:107]
	v_pk_mul_f32 v[4:5], v[192:193], v[104:105]
	global_store_dwordx4 v[112:113], v[0:3], off
	global_store_dwordx4 v[112:113], v[4:7], off offset:16
	s_nop 0
	s_nop 0
	s_nop 0
	s_nop 0
	v_pk_mul_f32 v[2:3], v[102:103], v[198:199]
	v_pk_mul_f32 v[0:1], v[100:101], v[196:197]
	s_nop 0
	v_pk_mul_f32 v[6:7], v[98:99], v[202:203]
	v_pk_mul_f32 v[4:5], v[96:97], v[200:201]
	global_store_dwordx4 v[112:113], v[0:3], off offset:512
	global_store_dwordx4 v[112:113], v[4:7], off offset:528
	s_nop 0
	s_nop 0
	s_nop 0
	v_add_u32_e32 v96, s39, v169
	v_ashrrev_i32_e32 v97, 31, v96
	v_lshlrev_b64 v[96:97], 13, v[96:97]
	v_lshl_add_u64 v[96:97], s[12:13], 0, v[96:97]
	v_lshl_add_u64 v[96:97], v[96:97], 0, v[158:159]
	s_nop 0
	v_pk_mul_f32 v[2:3], v[190:191], v[94:95]
	v_pk_mul_f32 v[0:1], v[188:189], v[92:93]
	s_nop 0
	v_pk_mul_f32 v[6:7], v[194:195], v[90:91]
	v_pk_mul_f32 v[4:5], v[192:193], v[88:89]
	global_store_dwordx4 v[96:97], v[0:3], off
	global_store_dwordx4 v[96:97], v[4:7], off offset:16
	s_nop 0
	s_nop 0
	s_nop 0
	s_nop 0
	v_pk_mul_f32 v[2:3], v[86:87], v[198:199]
	v_pk_mul_f32 v[0:1], v[84:85], v[196:197]
	s_nop 0
	v_pk_mul_f32 v[6:7], v[82:83], v[202:203]
	v_pk_mul_f32 v[4:5], v[80:81], v[200:201]
	global_store_dwordx4 v[96:97], v[0:3], off offset:512
	global_store_dwordx4 v[96:97], v[4:7], off offset:528
	s_nop 0
	s_nop 0
	s_nop 0
	v_add_u32_e32 v80, s39, v171
	v_ashrrev_i32_e32 v81, 31, v80
	v_lshlrev_b64 v[80:81], 13, v[80:81]
	v_lshl_add_u64 v[80:81], s[12:13], 0, v[80:81]
	v_lshl_add_u64 v[80:81], v[80:81], 0, v[158:159]
	s_nop 0
	v_pk_mul_f32 v[2:3], v[190:191], v[78:79]
	v_pk_mul_f32 v[0:1], v[188:189], v[76:77]
	s_nop 0
	v_pk_mul_f32 v[6:7], v[194:195], v[74:75]
	v_pk_mul_f32 v[4:5], v[192:193], v[72:73]
	global_store_dwordx4 v[80:81], v[0:3], off
	global_store_dwordx4 v[80:81], v[4:7], off offset:16
	s_nop 0
	s_nop 0
	s_nop 0
	s_nop 0
	v_pk_mul_f32 v[2:3], v[70:71], v[198:199]
	v_pk_mul_f32 v[0:1], v[68:69], v[196:197]
	s_nop 0
	v_pk_mul_f32 v[6:7], v[66:67], v[202:203]
	v_pk_mul_f32 v[4:5], v[64:65], v[200:201]
	global_store_dwordx4 v[80:81], v[0:3], off offset:512
	global_store_dwordx4 v[80:81], v[4:7], off offset:528
	s_nop 0
	s_nop 0
	s_nop 0
	v_add_u32_e32 v64, s39, v173
	v_ashrrev_i32_e32 v65, 31, v64
	v_lshlrev_b64 v[64:65], 13, v[64:65]
	v_lshl_add_u64 v[64:65], s[12:13], 0, v[64:65]
	v_lshl_add_u64 v[64:65], v[64:65], 0, v[158:159]
	s_nop 0
	v_pk_mul_f32 v[2:3], v[190:191], v[62:63]
	v_pk_mul_f32 v[0:1], v[188:189], v[60:61]
	s_nop 0
	v_pk_mul_f32 v[6:7], v[194:195], v[58:59]
	v_pk_mul_f32 v[4:5], v[192:193], v[56:57]
	global_store_dwordx4 v[64:65], v[0:3], off
	global_store_dwordx4 v[64:65], v[4:7], off offset:16
	s_nop 0
	s_nop 0
	s_nop 0
	s_nop 0
	v_pk_mul_f32 v[2:3], v[54:55], v[198:199]
	v_pk_mul_f32 v[0:1], v[52:53], v[196:197]
	s_nop 0
	v_pk_mul_f32 v[6:7], v[50:51], v[202:203]
	v_pk_mul_f32 v[4:5], v[48:49], v[200:201]
	global_store_dwordx4 v[64:65], v[0:3], off offset:512
	global_store_dwordx4 v[64:65], v[4:7], off offset:528
	s_nop 0
	s_nop 0
	s_nop 0
	v_add_u32_e32 v48, s39, v174
	v_ashrrev_i32_e32 v49, 31, v48
	v_lshlrev_b64 v[48:49], 13, v[48:49]
	v_lshl_add_u64 v[48:49], s[12:13], 0, v[48:49]
	v_lshl_add_u64 v[48:49], v[48:49], 0, v[158:159]
	s_nop 0
	v_pk_mul_f32 v[2:3], v[190:191], v[46:47]
	v_pk_mul_f32 v[0:1], v[188:189], v[44:45]
	s_nop 0
	v_pk_mul_f32 v[6:7], v[194:195], v[42:43]
	v_pk_mul_f32 v[4:5], v[192:193], v[40:41]
	global_store_dwordx4 v[48:49], v[0:3], off
	global_store_dwordx4 v[48:49], v[4:7], off offset:16
	s_nop 0
	s_nop 0
	s_nop 0
	s_nop 0
	v_pk_mul_f32 v[2:3], v[38:39], v[198:199]
	v_pk_mul_f32 v[0:1], v[36:37], v[196:197]
	s_nop 0
	v_pk_mul_f32 v[6:7], v[34:35], v[202:203]
	v_pk_mul_f32 v[4:5], v[32:33], v[200:201]
	global_store_dwordx4 v[48:49], v[0:3], off offset:512
	global_store_dwordx4 v[48:49], v[4:7], off offset:528
	s_nop 0
	s_nop 0
	s_nop 0
	v_add_u32_e32 v32, s39, v175
	v_ashrrev_i32_e32 v33, 31, v32
	v_lshlrev_b64 v[32:33], 13, v[32:33]
	v_lshl_add_u64 v[32:33], s[12:13], 0, v[32:33]
	v_lshl_add_u64 v[32:33], v[32:33], 0, v[158:159]
	s_nop 0
	v_pk_mul_f32 v[2:3], v[190:191], v[30:31]
	v_pk_mul_f32 v[0:1], v[188:189], v[28:29]
	s_nop 0
	v_pk_mul_f32 v[6:7], v[194:195], v[26:27]
	v_pk_mul_f32 v[4:5], v[192:193], v[24:25]
	global_store_dwordx4 v[32:33], v[0:3], off
	global_store_dwordx4 v[32:33], v[4:7], off offset:16
	s_nop 0
	s_nop 0
	s_nop 0
	v_pk_mul_f32 v[24:25], v[152:153], v[170:171] op_sel_hi:[1,0]
	s_nop 0
	v_pk_mul_f32 v[2:3], v[22:23], v[198:199]
	v_pk_mul_f32 v[0:1], v[20:21], v[196:197]
	s_nop 0
	v_pk_mul_f32 v[6:7], v[18:19], v[202:203]
	v_pk_mul_f32 v[4:5], v[16:17], v[200:201]
	global_store_dwordx4 v[32:33], v[0:3], off offset:512
	global_store_dwordx4 v[32:33], v[4:7], off offset:528
	s_nop 0
	s_nop 0
	s_nop 0
	v_add_u32_e32 v16, s39, v176
	v_ashrrev_i32_e32 v17, 31, v16
	v_lshlrev_b64 v[16:17], 13, v[16:17]
	v_lshl_add_u64 v[16:17], s[12:13], 0, v[16:17]
	v_pk_mul_f32 v[18:19], v[154:155], v[170:171] op_sel_hi:[1,0]
	v_pk_mul_f32 v[20:21], v[156:157], v[170:171] op_sel_hi:[1,0]
	v_lshl_add_u64 v[16:17], v[16:17], 0, v[158:159]
	v_pk_mul_f32 v[22:23], v[150:151], v[170:171] op_sel_hi:[1,0]
	s_nop 0
	v_pk_mul_f32 v[2:3], v[190:191], v[18:19]
	v_pk_mul_f32 v[0:1], v[188:189], v[20:21]
	s_nop 0
	v_pk_mul_f32 v[6:7], v[194:195], v[22:23]
	v_pk_mul_f32 v[4:5], v[192:193], v[24:25]
	global_store_dwordx4 v[16:17], v[0:3], off
	global_store_dwordx4 v[16:17], v[4:7], off offset:16
	s_nop 0
	s_nop 0
	s_nop 0
	s_nop 0
	v_pk_mul_f32 v[2:3], v[8:9], v[198:199]
	v_pk_mul_f32 v[0:1], v[10:11], v[196:197]
	s_nop 0
	v_pk_mul_f32 v[6:7], v[12:13], v[202:203]
	v_pk_mul_f32 v[4:5], v[14:15], v[200:201]
	global_store_dwordx4 v[16:17], v[0:3], off offset:512
	global_store_dwordx4 v[16:17], v[4:7], off offset:528
	s_cbranch_vccnz .LBB0_1270
	s_andn2_b64 vcc, exec, s[26:27]
	s_cbranch_vccnz .LBB0_1269
	s_barrier
	s_branch .LBB0_1269
